# up-GEMM tile order WGM 8 -> 16 (16 row panels x 2 column tiles per XCD round), on top of v40
# baseline (speedup 1.0000x reference)
; __device__ __forceinline__ int otid() { int t = threadIdx.x; asm volatile("" : "+v"(t)); return t; }
; #define PG8_LAS __attribute__((address_space(3)))
;     __host__ __device__ bool next(int i, Unit& u) const {
;     ...
;         int wgid = (int)L; { const int q = nwg / NXCD, r = nwg % NXCD, xcd = wgid % NXCD, off = wgid / NXCD; wgid = (xcd < r ? xcd * (q + 1) : r * (q + 1) + (xcd - r) * q) + off; }
;         const int nig = WGM * nN, gid = wgid / nig, fm = gid * WGM, gsz = (nM - fm) < WGM ? (nM - fm) : WGM;
;         u.pm = fm + ((wgid % nig) % gsz); u.pn = (wgid % nig) / gsz; return true;
;     }
; __device__ __forceinline__ unsigned cvt_pk_bf16(float lo, float hi) { unsigned r; asm volatile("v_cvt_pk_bf16_f32 %0, %1, %2" : "=v"(r) : "v"(lo), "v"(hi)); return r; }
; template <class Epi, class Sched, bool ALIGN_EPI = false, bool SP2 = false>
; __device__ __forceinline__ void gemm_phase(PG8_LAS unsigned char* lds, const Gemm g, const Sched& S, const Epi& E) {
;     const int tid = otid(), wid = __builtin_amdgcn_readfirstlane(tid >> 6), lane = tid & 63, wr = wid >> 2, wc = wid & 3, fr = lane & 15, fq = lane >> 4;
;     const int K = g.K, nt = K / BK;
;     unsigned voffA[2], voffB[2];
; #pragma unroll
;     for (int i = 0; i < 2; ++i) { int R, C; stage_rc(tid * 16 + i * 8192, R, C); const int Rb = Epi::PERM ? ((R & ~31) + perm32(R & 31)) : R;
;         voffA[i] = (unsigned)(R * g.lda + C) * 2u; voffB[i] = (unsigned)(Rb * K + C) * 2u; }
;     const size_t kstep = (size_t)(BK * 2);
;     const size_t hstepB = (size_t)HALF * K * 2, hstepA = (size_t)HALF * g.lda * 2;
;     const size_t tstepA = 2 * hstepA, tstepB = 2 * hstepB;
;     const unsigned ldsw = (unsigned)wid * 1024u;
;     const int aoff = lds_byte(wr * 64 + fr, fq * 8), boff = lds_byte(wc * 32 + fr, fq * 8);
;     ...
;     const char* cA = (const char*)g.A + (size_t)cur.pm * tstepA; const char* cB = (const char*)g.Bt + (size_t)cur.pn * tstepB;
;     S.a_ready(cur);
;     if constexpr (SP2) {
;         PG8_STAGE(PG8_SB(0, 0), cB, voffB); PG8_STAGE(PG8_SB(0, 1), cB + hstepB, voffB); PG8_STAGE(PG8_SA(0, 0), cA, voffA); PG8_STAGE(PG8_SA(0, 1), cA + hstepA, voffA);
;         if (wr == 1) PG8_BAR;
;         PG8_WAIT_V(2); PG8_BAR;
;         PG8_STAGE(PG8_SB(1, 0), cB + kstep, voffB); PG8_STAGE(PG8_SA(1, 0), cA + kstep, voffA); PG8_STAGE(PG8_SB(1, 1), cB + hstepB + kstep, voffB);
;         PG8_WAIT_V(6); PG8_BAR;
.LBB0_434:
	s_andn2_b64 vcc, exec, s[8:9]
	s_cbranch_vccnz .LBB0_451
	s_and_b64 s[4:5], exec, s[60:61]
	s_movk_i32 s2, 0x108
	s_cselect_b32 s2, s2, 0x100
	s_mov_b32 s4, s36
	s_mul_i32 s34, s2, 22
	v_mov_b32_e32 v8, v163
	s_cmp_ge_i32 s4, s34
	v_readfirstlane_b32 s9, v8
	s_cbranch_scc1 .LBB0_451
	s_waitcnt vmcnt(0)
	v_lshlrev_b32_e32 v0, 4, v8
	v_add_u32_e32 v1, 0x2000, v0
	s_waitcnt lgkmcnt(0)
	v_ashrrev_i32_e32 v2, 31, v1
	v_lshrrev_b32_e32 v2, 22, v2
	v_add_u32_e32 v2, v1, v2
	v_ashrrev_i32_e32 v9, 10, v2
	v_mul_i32_i24_e32 v2, 0x400, v9
	v_sub_u32_e32 v1, v1, v2
	v_lshrrev_b32_e32 v2, 4, v1
	v_bitop3_b32 v1, v2, v1, 32 bitop3:0x6c
	v_ashrrev_i32_e32 v2, 31, v1
	v_lshrrev_b32_e32 v2, 26, v2
	v_add_u32_e32 v2, v1, v2
	v_lshlrev_b32_e32 v3, 3, v9
	v_ashrrev_i32_e32 v10, 6, v2
	v_and_b32_e32 v3, -16, v3
	v_add_u32_e32 v3, v10, v3
	v_and_b32_e32 v4, 3, v10
	s_mov_b32 s8, 0x1fffe0
	v_lshrrev_b32_e32 v5, 2, v3
	v_lshlrev_b32_e32 v6, 1, v3
	v_and_b32_e32 v2, 0xc0, v2
	v_and_or_b32 v4, v3, s8, v4
	v_and_b32_e32 v5, 4, v5
	v_and_b32_e32 v6, 24, v6
	v_sub_u32_e32 v1, v1, v2
	v_or3_b32 v4, v4, v5, v6
	v_lshlrev_b32_e32 v5, 5, v9
	v_ashrrev_i16_sdwa v1, v246, sext(v1) dst_sel:DWORD dst_unused:UNUSED_PAD src0_sel:DWORD src1_sel:BYTE_0
	v_and_b32_e32 v5, 32, v5
	v_bfe_i32 v11, v1, 0, 16
	v_add_lshl_u32 v1, v5, v11, 1
	v_lshl_add_u32 v128, v4, 11, v1
	v_lshl_add_u32 v130, v3, 11, v1
	v_bfe_i32 v1, v8, 27, 1
	v_lshrrev_b32_e32 v1, 22, v1
	v_add_u32_e32 v1, v0, v1
	v_and_b32_e32 v1, 0xfffffc00, v1
	v_sub_u32_e32 v0, v0, v1
	v_lshrrev_b32_e32 v1, 4, v0
	v_bitop3_b32 v1, v1, v0, 32 bitop3:0x6c
	v_ashrrev_i32_e32 v0, 31, v0
	v_lshrrev_b32_e32 v0, 26, v0
	v_add_u32_e32 v0, v1, v0
	v_ashrrev_i32_e32 v12, 6, v0
	v_ashrrev_i32_e32 v0, 31, v8
	v_lshrrev_b32_e32 v0, 26, v0
	s_lshl_b64 s[6:7], s[62:63], 1
	v_add_u32_e32 v0, v8, v0
	s_add_u32 s5, s54, s6
	v_ashrrev_i32_e32 v13, 6, v0
	s_addc_u32 s6, s55, s7
	v_lshlrev_b32_e32 v0, 3, v13
	s_add_u32 s5, s5, 0xc00000
	v_and_b32_e32 v0, -16, v0
	s_addc_u32 s6, s6, 0
	v_add_u32_e32 v0, v12, v0
	v_and_b32_e32 v2, 3, v12
	s_ashr_i32 s17, s4, 31
	v_and_or_b32 v2, v0, s8, v2
	s_lshr_b32 s8, s17, 29
	s_add_i32 s8, s4, s8
	s_ashr_i32 s13, s9, 6
	s_lshr_b32 s16, s34, 3
	s_ashr_i32 s10, s8, 3
	s_and_b32 s8, s8, -8
	s_ashr_i32 s12, s9, 8
	s_lshl_b32 s7, s13, 10
	s_sub_i32 s8, s4, s8
	s_or_b32 s18, s16, 1
	s_cmp_lt_i32 s8, 0
	s_cselect_b32 s11, s18, s16
	s_mul_i32 s8, s11, s8
	v_lshrrev_b32_e32 v3, 2, v0
	v_lshlrev_b32_e32 v4, 1, v0
	s_add_i32 s8, s8, s10
	v_and_b32_e32 v3, 4, v3
	v_and_b32_e32 v4, 24, v4
	s_mul_hi_i32 s10, s8, 0x2e8ba2e9
	v_or3_b32 v2, v2, v3, v4
	v_mul_i32_i24_e32 v4, 64, v12
	s_lshr_b32 s11, s10, 31
	s_ashr_i32 s10, s10, 6
	v_sub_u32_e32 v1, v1, v4
	s_add_i32 s10, s10, s11
	v_lshlrev_b32_e32 v3, 5, v13
	v_ashrrev_i16_sdwa v1, v246, sext(v1) dst_sel:DWORD dst_unused:UNUSED_PAD src0_sel:DWORD src1_sel:BYTE_0
	s_lshl_b32 s14, s10, 4
	v_and_b32_e32 v3, 32, v3
	v_bfe_i32 v14, v1, 0, 16
	s_sub_i32 s11, s2, s14
	v_add_lshl_u32 v1, v3, v14, 1
	s_min_i32 s15, s11, 16
	v_lshl_add_u32 v132, v0, 11, v1
	v_cvt_f32_i32_e32 v0, s15
	s_mulk_i32 s10, 0x160
	s_sub_i32 s19, s8, s10
	v_lshl_add_u32 v144, v2, 11, v1
	v_cvt_f32_i32_e32 v1, s19
	v_rcp_iflag_f32_e32 v2, v0
	s_xor_b32 s8, s19, s15
	s_ashr_i32 s8, s8, 30
	s_or_b32 s8, s8, 1
	v_mul_f32_e32 v2, v1, v2
	v_trunc_f32_e32 v2, v2
	v_fma_f32 v1, -v2, v0, v1
	v_cvt_i32_f32_e32 v2, v2
	v_cmp_ge_f32_e64 s[10:11], |v1|, |v0|
	s_and_b64 s[10:11], s[10:11], exec
	s_cselect_b32 s8, s8, 0
	v_readfirstlane_b32 s10, v2
	s_add_i32 s8, s10, s8
	s_mul_i32 s10, s8, s15
	s_sub_i32 s10, s19, s10
	s_sext_i32_i16 s10, s10
	s_add_i32 s62, s14, s10
	s_ashr_i32 s63, s62, 31
	s_bfe_i64 s[14:15], s[8:9], 0x100000
	s_lshl_b64 s[10:11], s[62:63], 19
	s_lshl_b64 s[14:15], s[14:15], 19
	s_add_u32 s64, s5, s14
	s_addc_u32 s65, s6, s15
	s_add_i32 s19, s7, 0
	s_add_i32 m0, s19, 0x10000
	s_load_dword s37, s[26:27], 0x0
	global_load_lds_dwordx4 v144, s[64:65]
	s_add_i32 m0, s19, 0x12000
	s_add_u32 s14, s64, 0x40000
	global_load_lds_dwordx4 v128, s[64:65]
	s_addc_u32 s15, s65, 0
	s_add_i32 m0, s19, 0x14000
	v_mov_b32_e32 v129, v145
	global_load_lds_dwordx4 v144, s[14:15]
	s_add_i32 m0, s19, 0x16000
	s_add_u32 s66, s56, s10
	s_addc_u32 s67, s57, s11
	s_add_i32 s24, s19, 0x2000
	global_load_lds_dwordx4 v128, s[14:15]
	s_mov_b32 m0, s19
	s_add_u32 s10, s66, 0x40000
	global_load_lds_dwordx4 v132, s[66:67]
	s_mov_b32 m0, s24
	s_addc_u32 s11, s67, 0
	s_add_i32 s25, s19, 0x4000
	global_load_lds_dwordx4 v130, s[66:67]
	s_mov_b32 m0, s25
	s_add_i32 s31, s19, 0x6000
	global_load_lds_dwordx4 v132, s[10:11]
	s_mov_b32 m0, s31
	v_mov_b32_e32 v133, v145
	global_load_lds_dwordx4 v130, s[10:11]
	v_mov_b32_e32 v131, v145
	s_cmp_eq_u32 s12, 1
	v_lshl_add_u64 v[6:7], s[64:65], 0, v[144:145]
	v_lshl_add_u64 v[4:5], s[64:65], 0, v[128:129]
	v_lshl_add_u64 v[0:1], s[66:67], 0, v[132:133]
	s_cselect_b64 s[10:11], -1, 0
	s_cmp_lg_u32 s12, 1
	v_lshl_add_u64 v[2:3], s[66:67], 0, v[130:131]
	s_cbranch_scc1 .LBB0_438
	s_barrier

; #define PG8_STAGE(bufoff, gbase, voff) do { _Pragma("unroll") for (int _i = 0; _i < 2; ++_i) \
;         __builtin_amdgcn_global_load_lds((const unsigned*)((const char*)(gbase) + (voff)[_i]), (PG8_LAS unsigned*)(lds + (bufoff) + ldsw + _i * 8192), 16, 0, 0); } while (0)
; #define PG8_LDA(dst, b, h) do { _Pragma("unroll") for (int m = 0; m < 4; ++m) _Pragma("unroll") for (int k = 0; k < 2; ++k) dst[m][k] = *(const PG8_LAS bf16x8*)(lds + PG8_SA(b, h) + aoff + m * 2048 + k * 1024); } while (0)
; #define PG8_LDB(dst, b, h) do { _Pragma("unroll") for (int n = 0; n < 2; ++n) _Pragma("unroll") for (int k = 0; k < 2; ++k) dst[n][k] = *(const PG8_LAS bf16x8*)(lds + PG8_SB(b, h) + boff + n * 2048 + k * 1024); } while (0)
; #define PG8_MMA(ai, bj, At, Bt) do { __builtin_amdgcn_s_setprio(1); _Pragma("unroll") for (int m = 0; m < 4; ++m) _Pragma("unroll") for (int n = 0; n < 2; ++n) _Pragma("unroll") for (int k = 0; k < 2; ++k) \
;         acc[ai][bj][m][n] = __builtin_amdgcn_mfma_f32_16x16x32_bf16(Bt[n][k], At[m][k], acc[ai][bj][m][n], 0, 0, 0); __builtin_amdgcn_s_setprio(0); } while (0)
; #define PG8_WAIT_V(n) asm volatile("s_waitcnt vmcnt(" #n ")" ::: "memory")
; #define PG8_WAIT_L(n) asm volatile("s_waitcnt lgkmcnt(" #n ")" ::: "memory")
; #define PG8_BAR __builtin_amdgcn_s_barrier()
; #define PG8_SCHED __builtin_amdgcn_sched_barrier(0)
; template <class Epi, class Sched, bool ALIGN_EPI = false, bool SP2 = false>
; __device__ __forceinline__ void gemm_phase(PG8_LAS unsigned char* lds, const Gemm g, const Sched& S, const Epi& E) {
;     ...
;         const bool has_next = S.next(ui + 1, nxt);
;         const char* nA = has_next ? (const char*)g.A + (size_t)nxt.pm * tstepA : cA; const char* nB = has_next ? (const char*)g.Bt + (size_t)nxt.pn * tstepB : cB;
;     ...
;             PG8_LDB(B0, 0, 0); PG8_LDB(B1, 0, 1); PG8_SCHED; PG8_LDA(At, 0, 0); PG8_STAGE(PG8_SA(1, 1), a1 + hstepA, voffA);
;             PG8_WAIT_V(8); PG8_WAIT_L(0); PG8_BAR; PG8_MMA(0, 0, At, B0); PG8_MMA(0, 1, At, B1); PG8_BAR; PG8_SCHED;
.LBB0_441:
.LBB0_443:
	s_mov_b64 s[86:87], s[66:67]
	s_mov_b64 s[88:89], s[64:65]
	s_add_u32 s76, s64, 0x100
	s_addc_u32 s77, s65, 0
	s_add_u32 s64, s66, 0x40080
	s_addc_u32 s65, s67, 0
	s_mov_b32 s78, -2
	s_add_u32 s50, s64, 0xfffc0080
	s_addc_u32 s51, s65, -1
	s_add_i32 s79, 0, 0x10000
	s_cmp_eq_u32 s78, 12
	s_cselect_b32 s69, s21, s51
	s_cselect_b32 s68, s74, s50
	s_cselect_b32 s67, s15, s77
	s_cselect_b32 s66, s75, s76
	s_add_i32 s80, 0, 0x14000
	v_add_u32_e32 v156, s79, v143
	v_add_u32_e32 v160, s80, v143
	ds_read_b128 v[138:141], v156
	ds_read_b128 v[148:151], v156 offset:1024
	ds_read_b128 v[152:155], v156 offset:2048
	ds_read_b128 v[156:159], v156 offset:3072
	ds_read_b128 v[188:191], v160
	ds_read_b128 v[192:195], v160 offset:1024
	ds_read_b128 v[196:199], v160 offset:2048
	ds_read_b128 v[200:203], v160 offset:3072
	v_lshl_add_u64 v[160:161], s[64:65], 0, v[136:137]
	s_add_i32 m0, s19, 0xc000
	ds_read_b128 v[204:207], v147
	ds_read_b128 v[208:211], v147 offset:1024
	ds_read_b128 v[212:215], v147 offset:2048
	ds_read_b128 v[216:219], v147 offset:3072
	ds_read_b128 v[220:223], v147 offset:4096
	ds_read_b128 v[224:227], v147 offset:5120
	ds_read_b128 v[228:231], v147 offset:6144
	ds_read_b128 v[232:235], v147 offset:7168
	global_load_lds_dwordx4 v[160:161], off
	v_lshl_add_u64 v[160:161], s[64:65], 0, v[134:135]
	s_add_i32 m0, s19, 0xe000
	s_nop 0
	global_load_lds_dwordx4 v[160:161], off
	s_waitcnt vmcnt(8)
	s_waitcnt lgkmcnt(0)
	s_barrier
	s_setprio 1
	s_waitcnt lgkmcnt(0)
	v_mfma_f32_16x16x32_bf16 v[124:127], v[138:141], v[204:207], 0
	s_add_i32 s73, s73, 1
	s_mul_i32 s8, s73, s72
	s_mul_hi_u32 s9, s73, s37
	v_mfma_f32_16x16x32_bf16 v[116:119], v[152:155], v[204:207], 0
	s_add_i32 s9, s9, s8
	s_mul_i32 s8, s73, s37
	s_add_u32 s22, s8, s4
	v_mfma_f32_16x16x32_bf16 v[108:111], v[138:141], v[212:215], 0
	s_addc_u32 s23, s9, s17
	v_mov_b64_e32 v[0:1], s[34:35]
	v_cmp_lt_i64_e64 s[8:9], s[22:23], v[0:1]
	v_mfma_f32_16x16x32_bf16 v[100:103], v[152:155], v[212:215], 0
	s_ashr_i32 s14, s22, 31
	s_lshr_b32 s14, s14, 29
	s_add_i32 s14, s22, s14
	v_mfma_f32_16x16x32_bf16 v[92:95], v[138:141], v[220:223], 0
	s_ashr_i32 s15, s14, 3
	s_and_b32 s14, s14, -8
	s_sub_i32 s14, s22, s14
	v_mfma_f32_16x16x32_bf16 v[84:87], v[152:155], v[220:223], 0
	s_cmp_lt_i32 s14, 0
	s_cselect_b32 s20, s18, s16
	s_mul_i32 s14, s20, s14
	v_mfma_f32_16x16x32_bf16 v[76:79], v[138:141], v[228:231], 0
	s_add_i32 s14, s14, s15
	s_mul_hi_i32 s15, s14, 0x2e8ba2e9
	s_lshr_b32 s20, s15, 31
	v_mfma_f32_16x16x32_bf16 v[68:71], v[152:155], v[228:231], 0
	s_ashr_i32 s15, s15, 6
	s_add_i32 s15, s15, s20
	s_lshl_b32 s20, s15, 4
	v_mfma_f32_16x16x32_bf16 v[124:127], v[148:151], v[208:211], v[124:127]
	s_sub_i32 s21, s2, s20
	s_min_i32 s21, s21, 16
	s_abs_i32 s22, s21
	v_mfma_f32_16x16x32_bf16 v[116:119], v[156:159], v[208:211], v[116:119]
	v_cvt_f32_u32_e32 v0, s22
	s_sub_i32 s50, 0, s22
	s_mulk_i32 s15, 0x160
	v_mfma_f32_16x16x32_bf16 v[108:111], v[148:151], v[216:219], v[108:111]
	s_sub_i32 s15, s14, s15
	v_rcp_iflag_f32_e32 v0, v0
	s_abs_i32 s14, s15
	v_mfma_f32_16x16x32_bf16 v[100:103], v[156:159], v[216:219], v[100:103]
	s_xor_b32 s23, s15, s21
	s_ashr_i32 s23, s23, 31
	v_mul_f32_e32 v0, 0x4f7ffffe, v0
	v_mfma_f32_16x16x32_bf16 v[92:95], v[148:151], v[224:227], v[92:95]
	v_cvt_u32_f32_e32 v0, v0
	s_nop 0
	v_readfirstlane_b32 s51, v0
	v_mfma_f32_16x16x32_bf16 v[84:87], v[156:159], v[224:227], v[84:87]
	s_mul_i32 s50, s50, s51
	s_mul_hi_u32 s50, s51, s50
	s_add_i32 s51, s51, s50
	v_mfma_f32_16x16x32_bf16 v[76:79], v[148:151], v[232:235], v[76:79]
	s_mul_hi_u32 s50, s14, s51
	s_mul_i32 s51, s50, s22
	s_sub_i32 s14, s14, s51
	v_mfma_f32_16x16x32_bf16 v[68:71], v[156:159], v[232:235], v[68:71]
	s_add_i32 s60, s50, 1
	s_sub_i32 s51, s14, s22
	s_cmp_ge_u32 s14, s22
	s_setprio 0
	s_setprio 1
	v_mfma_f32_16x16x32_bf16 v[120:123], v[188:191], v[204:207], 0
	s_cselect_b32 s50, s60, s50
	s_cselect_b32 s14, s51, s14
	s_add_i32 s51, s50, 1
	v_mfma_f32_16x16x32_bf16 v[112:115], v[196:199], v[204:207], 0
	s_cmp_ge_u32 s14, s22
	s_cselect_b32 s14, s51, s50
	s_xor_b32 s14, s14, s23
	v_mfma_f32_16x16x32_bf16 v[104:107], v[188:191], v[212:215], 0
	s_sub_i32 s14, s14, s23
	s_mul_i32 s21, s14, s21
	s_sub_i32 s15, s15, s21
	v_mfma_f32_16x16x32_bf16 v[96:99], v[196:199], v[212:215], 0
	s_add_i32 s20, s15, s20
	s_ashr_i32 s21, s20, 31
	s_lshl_b64 s[22:23], s[20:21], 19
	v_mfma_f32_16x16x32_bf16 v[88:91], v[188:191], v[220:223], 0
	s_add_u32 s22, s56, s22
	s_addc_u32 s23, s57, s23
	s_and_b64 s[50:51], s[8:9], exec
	v_mfma_f32_16x16x32_bf16 v[80:83], v[196:199], v[220:223], 0
	s_cselect_b32 s21, s23, s87
	s_cselect_b32 s74, s22, s86
	s_ashr_i32 s15, s14, 31
	v_mfma_f32_16x16x32_bf16 v[72:75], v[188:191], v[228:231], 0
	s_lshl_b64 s[50:51], s[14:15], 19
	s_add_u32 s60, s5, s50
	s_addc_u32 s61, s6, s51
	v_mfma_f32_16x16x32_bf16 v[64:67], v[196:199], v[228:231], 0
	s_and_b64 s[50:51], s[8:9], exec
	s_cselect_b32 s15, s61, s89
	s_cselect_b32 s75, s60, s88
	v_mfma_f32_16x16x32_bf16 v[120:123], v[192:195], v[208:211], v[120:123]
	v_mfma_f32_16x16x32_bf16 v[112:115], v[200:203], v[208:211], v[112:115]
	v_mfma_f32_16x16x32_bf16 v[104:107], v[192:195], v[216:219], v[104:107]
	v_mfma_f32_16x16x32_bf16 v[96:99], v[200:203], v[216:219], v[96:99]
	v_mfma_f32_16x16x32_bf16 v[88:91], v[192:195], v[224:227], v[88:91]
	v_mfma_f32_16x16x32_bf16 v[80:83], v[200:203], v[224:227], v[80:83]
	v_mfma_f32_16x16x32_bf16 v[72:75], v[192:195], v[232:235], v[72:75]
	v_mfma_f32_16x16x32_bf16 v[64:67], v[200:203], v[232:235], v[64:67]
	s_setprio 0
	s_barrier
; #define PG8_STAGE(bufoff, gbase, voff) do { _Pragma("unroll") for (int _i = 0; _i < 2; ++_i) \
;         __builtin_amdgcn_global_load_lds((const unsigned*)((const char*)(gbase) + (voff)[_i]), (PG8_LAS unsigned*)(lds + (bufoff) + ldsw + _i * 8192), 16, 0, 0); } while (0)
; #define PG8_LDA(dst, b, h) do { _Pragma("unroll") for (int m = 0; m < 4; ++m) _Pragma("unroll") for (int k = 0; k < 2; ++k) dst[m][k] = *(const PG8_LAS bf16x8*)(lds + PG8_SA(b, h) + aoff + m * 2048 + k * 1024); } while (0)
; #define PG8_LDB(dst, b, h) do { _Pragma("unroll") for (int n = 0; n < 2; ++n) _Pragma("unroll") for (int k = 0; k < 2; ++k) dst[n][k] = *(const PG8_LAS bf16x8*)(lds + PG8_SB(b, h) + boff + n * 2048 + k * 1024); } while (0)
; #define PG8_MMA(ai, bj, At, Bt) do { __builtin_amdgcn_s_setprio(1); _Pragma("unroll") for (int m = 0; m < 4; ++m) _Pragma("unroll") for (int n = 0; n < 2; ++n) _Pragma("unroll") for (int k = 0; k < 2; ++k) \
;         acc[ai][bj][m][n] = __builtin_amdgcn_mfma_f32_16x16x32_bf16(Bt[n][k], At[m][k], acc[ai][bj][m][n], 0, 0, 0); __builtin_amdgcn_s_setprio(0); } while (0)
; #define PG8_WAIT_V(n) asm volatile("s_waitcnt vmcnt(" #n ")" ::: "memory")
; #define PG8_WAIT_L(n) asm volatile("s_waitcnt lgkmcnt(" #n ")" ::: "memory")
; #define PG8_BAR __builtin_amdgcn_s_barrier()
; #define PG8_SCHED __builtin_amdgcn_sched_barrier(0)
; template <class Epi, class Sched, bool ALIGN_EPI = false, bool SP2 = false>
; __device__ __forceinline__ void gemm_phase(PG8_LAS unsigned char* lds, const Gemm g, const Sched& S, const Epi& E) {
;     ...
;             PG8_WAIT_V(8); PG8_WAIT_L(0); PG8_BAR; PG8_MMA(0, 0, At, B0); PG8_MMA(0, 1, At, B1); PG8_BAR; PG8_SCHED;
;             PG8_LDA(At, 0, 1); PG8_STAGE(PG8_SB(0, 0), b2, voffB); PG8_STAGE(PG8_SB(0, 1), b2 + hstepB, voffB); PG8_STAGE(PG8_SA(0, 0), a2, voffA);
;             PG8_WAIT_V(8); PG8_WAIT_L(0); PG8_BAR; PG8_MMA(1, 0, At, B0); PG8_MMA(1, 1, At, B1); PG8_BAR; PG8_SCHED;
;             PG8_LDB(B0, 1, 0); PG8_LDB(B1, 1, 1); PG8_SCHED; PG8_LDA(At, 1, 0); PG8_STAGE(PG8_SA(0, 1), a2 + hstepA, voffA);
;             PG8_WAIT_V(8); PG8_WAIT_L(0); PG8_BAR; PG8_MMA(0, 0, At, B0); PG8_MMA(0, 1, At, B1); PG8_BAR; PG8_SCHED;
	s_add_i32 s50, s79, s7
	v_lshl_add_u64 v[160:161], s[66:67], 0, v[144:145]
	s_mov_b32 m0, s50
	ds_read_b128 v[204:207], v147 offset:16384
	ds_read_b128 v[208:211], v147 offset:17408
	ds_read_b128 v[212:215], v147 offset:18432
	ds_read_b128 v[216:219], v147 offset:19456
	ds_read_b128 v[220:223], v147 offset:20480
	ds_read_b128 v[224:227], v147 offset:21504
	ds_read_b128 v[228:231], v147 offset:22528
	ds_read_b128 v[232:235], v147 offset:23552
	global_load_lds_dwordx4 v[160:161], off
	s_add_i32 m0, s50, 0x2000
	s_add_u32 s50, s66, 0x40000
	v_lshl_add_u64 v[174:175], s[66:67], 0, v[128:129]
	s_addc_u32 s51, s67, 0
	s_add_i32 s79, s80, s7
	global_load_lds_dwordx4 v[174:175], off
	v_lshl_add_u64 v[236:237], s[50:51], 0, v[144:145]
	s_mov_b32 m0, s79
	v_lshl_add_u64 v[238:239], s[68:69], 0, v[130:131]
	global_load_lds_dwordx4 v[236:237], off
	v_lshl_add_u64 v[236:237], s[50:51], 0, v[128:129]
	s_add_i32 m0, s79, 0x2000
	s_nop 0
	global_load_lds_dwordx4 v[236:237], off
	v_lshl_add_u64 v[236:237], s[68:69], 0, v[132:133]
	s_mov_b32 m0, s19
	s_nop 0
	global_load_lds_dwordx4 v[236:237], off
	s_mov_b32 m0, s24
	s_nop 0
	global_load_lds_dwordx4 v[238:239], off
	s_waitcnt vmcnt(8)
	s_waitcnt lgkmcnt(0)
	s_barrier
	s_setprio 1
	s_waitcnt lgkmcnt(0)
	v_mfma_f32_16x16x32_bf16 v[60:63], v[138:141], v[204:207], 0
	v_mfma_f32_16x16x32_bf16 v[52:55], v[152:155], v[204:207], 0
	v_mfma_f32_16x16x32_bf16 v[44:47], v[138:141], v[212:215], 0
	v_mfma_f32_16x16x32_bf16 v[36:39], v[152:155], v[212:215], 0
	v_mfma_f32_16x16x32_bf16 v[28:31], v[138:141], v[220:223], 0
	v_mfma_f32_16x16x32_bf16 v[20:23], v[152:155], v[220:223], 0
	v_mfma_f32_16x16x32_bf16 v[12:15], v[138:141], v[228:231], 0
	v_mfma_f32_16x16x32_bf16 v[4:7], v[152:155], v[228:231], 0
	v_mfma_f32_16x16x32_bf16 v[60:63], v[148:151], v[208:211], v[60:63]
	v_mfma_f32_16x16x32_bf16 v[52:55], v[156:159], v[208:211], v[52:55]
	v_mfma_f32_16x16x32_bf16 v[44:47], v[148:151], v[216:219], v[44:47]
	v_mfma_f32_16x16x32_bf16 v[36:39], v[156:159], v[216:219], v[36:39]
	v_mfma_f32_16x16x32_bf16 v[28:31], v[148:151], v[224:227], v[28:31]
	v_mfma_f32_16x16x32_bf16 v[20:23], v[156:159], v[224:227], v[20:23]
	v_mfma_f32_16x16x32_bf16 v[12:15], v[148:151], v[232:235], v[12:15]
	v_mfma_f32_16x16x32_bf16 v[4:7], v[156:159], v[232:235], v[4:7]
	s_setprio 0
	s_setprio 1
	v_mfma_f32_16x16x32_bf16 v[56:59], v[188:191], v[204:207], 0
	v_mfma_f32_16x16x32_bf16 v[48:51], v[196:199], v[204:207], 0
	v_mfma_f32_16x16x32_bf16 v[40:43], v[188:191], v[212:215], 0
	v_mfma_f32_16x16x32_bf16 v[32:35], v[196:199], v[212:215], 0
	v_mfma_f32_16x16x32_bf16 v[24:27], v[188:191], v[220:223], 0
	v_mfma_f32_16x16x32_bf16 v[16:19], v[196:199], v[220:223], 0
	v_mfma_f32_16x16x32_bf16 v[8:11], v[188:191], v[228:231], 0
	v_mfma_f32_16x16x32_bf16 v[0:3], v[196:199], v[228:231], 0
	v_mfma_f32_16x16x32_bf16 v[56:59], v[192:195], v[208:211], v[56:59]
	v_mfma_f32_16x16x32_bf16 v[48:51], v[200:203], v[208:211], v[48:51]
	v_mfma_f32_16x16x32_bf16 v[40:43], v[192:195], v[216:219], v[40:43]
	v_mfma_f32_16x16x32_bf16 v[32:35], v[200:203], v[216:219], v[32:35]
	v_mfma_f32_16x16x32_bf16 v[24:27], v[192:195], v[224:227], v[24:27]
	v_mfma_f32_16x16x32_bf16 v[16:19], v[200:203], v[224:227], v[16:19]
	v_mfma_f32_16x16x32_bf16 v[8:11], v[192:195], v[232:235], v[8:11]
	v_mfma_f32_16x16x32_bf16 v[0:3], v[200:203], v[232:235], v[0:3]
	s_setprio 0
	s_barrier
	s_add_i32 s79, 0, 0x18000
	s_add_i32 s80, 0, 0x1c000
	v_add_u32_e32 v156, s79, v143
	v_add_u32_e32 v162, s80, v143
	ds_read_b128 v[138:141], v156
	ds_read_b128 v[148:151], v156 offset:1024
	ds_read_b128 v[152:155], v156 offset:2048
	ds_read_b128 v[156:159], v156 offset:3072
	ds_read_b128 v[188:191], v162
	ds_read_b128 v[192:195], v162 offset:1024
	ds_read_b128 v[196:199], v162 offset:2048
	ds_read_b128 v[200:203], v162 offset:3072
	s_add_u32 s50, s68, 0x40000
	s_addc_u32 s51, s69, 0
	s_mov_b32 m0, s25
	v_lshl_add_u64 v[240:241], s[50:51], 0, v[132:133]
	ds_read_b128 v[204:207], v147 offset:32768
	ds_read_b128 v[208:211], v147 offset:33792
	ds_read_b128 v[212:215], v147 offset:34816
	ds_read_b128 v[216:219], v147 offset:35840
	ds_read_b128 v[220:223], v147 offset:36864
	ds_read_b128 v[224:227], v147 offset:37888
	ds_read_b128 v[228:231], v147 offset:38912
	ds_read_b128 v[232:235], v147 offset:39936
	global_load_lds_dwordx4 v[240:241], off
	v_lshl_add_u64 v[240:241], s[50:51], 0, v[130:131]
	s_mov_b32 m0, s31
	s_nop 0
	global_load_lds_dwordx4 v[240:241], off
	s_waitcnt vmcnt(8)
	s_waitcnt lgkmcnt(0)
	s_barrier
; #define PG8_STAGE(bufoff, gbase, voff) do { _Pragma("unroll") for (int _i = 0; _i < 2; ++_i) \
;         __builtin_amdgcn_global_load_lds((const unsigned*)((const char*)(gbase) + (voff)[_i]), (PG8_LAS unsigned*)(lds + (bufoff) + ldsw + _i * 8192), 16, 0, 0); } while (0)
; #define PG8_LDA(dst, b, h) do { _Pragma("unroll") for (int m = 0; m < 4; ++m) _Pragma("unroll") for (int k = 0; k < 2; ++k) dst[m][k] = *(const PG8_LAS bf16x8*)(lds + PG8_SA(b, h) + aoff + m * 2048 + k * 1024); } while (0)
; #define PG8_MMA(ai, bj, At, Bt) do { __builtin_amdgcn_s_setprio(1); _Pragma("unroll") for (int m = 0; m < 4; ++m) _Pragma("unroll") for (int n = 0; n < 2; ++n) _Pragma("unroll") for (int k = 0; k < 2; ++k) \
;         acc[ai][bj][m][n] = __builtin_amdgcn_mfma_f32_16x16x32_bf16(Bt[n][k], At[m][k], acc[ai][bj][m][n], 0, 0, 0); __builtin_amdgcn_s_setprio(0); } while (0)
; #define PG8_WAIT_V(n) asm volatile("s_waitcnt vmcnt(" #n ")" ::: "memory")
; #define PG8_WAIT_L(n) asm volatile("s_waitcnt lgkmcnt(" #n ")" ::: "memory")
; #define PG8_BAR __builtin_amdgcn_s_barrier()
; #define PG8_SCHED __builtin_amdgcn_sched_barrier(0)
; template <class Epi, class Sched, bool ALIGN_EPI = false, bool SP2 = false>
; __device__ __forceinline__ void gemm_phase(PG8_LAS unsigned char* lds, const Gemm g, const Sched& S, const Epi& E) {
;     ...
;             PG8_WAIT_V(8); PG8_WAIT_L(0); PG8_BAR; PG8_MMA(0, 0, At, B0); PG8_MMA(0, 1, At, B1); PG8_BAR; PG8_SCHED;
;             PG8_LDA(At, 1, 1); PG8_STAGE(PG8_SB(1, 0), b3, voffB); PG8_STAGE(PG8_SB(1, 1), b3 + hstepB, voffB); PG8_STAGE(PG8_SA(1, 0), a3, voffA);
;             PG8_WAIT_V(8); PG8_WAIT_L(0); PG8_BAR; PG8_MMA(1, 0, At, B0); PG8_MMA(1, 1, At, B1); PG8_BAR; PG8_SCHED;
	s_setprio 1
	s_waitcnt lgkmcnt(0)
	v_mfma_f32_16x16x32_bf16 v[124:127], v[138:141], v[204:207], v[124:127]
	v_mfma_f32_16x16x32_bf16 v[116:119], v[152:155], v[204:207], v[116:119]
	v_mfma_f32_16x16x32_bf16 v[108:111], v[138:141], v[212:215], v[108:111]
	v_mfma_f32_16x16x32_bf16 v[100:103], v[152:155], v[212:215], v[100:103]
	v_mfma_f32_16x16x32_bf16 v[92:95], v[138:141], v[220:223], v[92:95]
	v_mfma_f32_16x16x32_bf16 v[84:87], v[152:155], v[220:223], v[84:87]
	v_mfma_f32_16x16x32_bf16 v[76:79], v[138:141], v[228:231], v[76:79]
	v_mfma_f32_16x16x32_bf16 v[68:71], v[152:155], v[228:231], v[68:71]
	v_mfma_f32_16x16x32_bf16 v[124:127], v[148:151], v[208:211], v[124:127]
	v_mfma_f32_16x16x32_bf16 v[116:119], v[156:159], v[208:211], v[116:119]
	v_mfma_f32_16x16x32_bf16 v[108:111], v[148:151], v[216:219], v[108:111]
	v_mfma_f32_16x16x32_bf16 v[100:103], v[156:159], v[216:219], v[100:103]
	v_mfma_f32_16x16x32_bf16 v[92:95], v[148:151], v[224:227], v[92:95]
	v_mfma_f32_16x16x32_bf16 v[84:87], v[156:159], v[224:227], v[84:87]
	v_mfma_f32_16x16x32_bf16 v[76:79], v[148:151], v[232:235], v[76:79]
	v_mfma_f32_16x16x32_bf16 v[68:71], v[156:159], v[232:235], v[68:71]
	s_setprio 0
	s_setprio 1
	v_mfma_f32_16x16x32_bf16 v[120:123], v[188:191], v[204:207], v[120:123]
	v_mfma_f32_16x16x32_bf16 v[112:115], v[196:199], v[204:207], v[112:115]
	v_mfma_f32_16x16x32_bf16 v[104:107], v[188:191], v[212:215], v[104:107]
	v_mfma_f32_16x16x32_bf16 v[96:99], v[196:199], v[212:215], v[96:99]
	v_mfma_f32_16x16x32_bf16 v[88:91], v[188:191], v[220:223], v[88:91]
	v_mfma_f32_16x16x32_bf16 v[80:83], v[196:199], v[220:223], v[80:83]
	v_mfma_f32_16x16x32_bf16 v[72:75], v[188:191], v[228:231], v[72:75]
	v_mfma_f32_16x16x32_bf16 v[64:67], v[196:199], v[228:231], v[64:67]
	v_mfma_f32_16x16x32_bf16 v[120:123], v[192:195], v[208:211], v[120:123]
	v_mfma_f32_16x16x32_bf16 v[112:115], v[200:203], v[208:211], v[112:115]
	v_mfma_f32_16x16x32_bf16 v[104:107], v[192:195], v[216:219], v[104:107]
	v_mfma_f32_16x16x32_bf16 v[96:99], v[200:203], v[216:219], v[96:99]
	v_mfma_f32_16x16x32_bf16 v[88:91], v[192:195], v[224:227], v[88:91]
	v_mfma_f32_16x16x32_bf16 v[80:83], v[200:203], v[224:227], v[80:83]
	v_mfma_f32_16x16x32_bf16 v[72:75], v[192:195], v[232:235], v[72:75]
	v_mfma_f32_16x16x32_bf16 v[64:67], v[200:203], v[232:235], v[64:67]
	s_setprio 0
	s_barrier
	s_add_i32 s50, s79, s7
	v_lshl_add_u64 v[160:161], v[160:161], 0, s[48:49]
	s_mov_b32 m0, s50
	ds_read_b128 v[204:207], v147 offset:49152
	ds_read_b128 v[208:211], v147 offset:50176
	ds_read_b128 v[212:215], v147 offset:51200
	ds_read_b128 v[216:219], v147 offset:52224
	ds_read_b128 v[220:223], v147 offset:53248
	ds_read_b128 v[224:227], v147 offset:54272
	ds_read_b128 v[228:231], v147 offset:55296
	ds_read_b128 v[232:235], v147 offset:56320
	global_load_lds_dwordx4 v[160:161], off
	s_add_i32 m0, s50, 0x2000
	s_add_u32 s50, s66, 0x40080
	v_lshl_add_u64 v[160:161], v[174:175], 0, s[48:49]
	s_addc_u32 s51, s67, 0
	s_add_i32 s66, s80, s7
	global_load_lds_dwordx4 v[160:161], off
	v_lshl_add_u64 v[160:161], s[50:51], 0, v[144:145]
	s_mov_b32 m0, s66
	s_nop 0
	global_load_lds_dwordx4 v[160:161], off
	v_lshl_add_u64 v[160:161], s[50:51], 0, v[128:129]
	s_add_i32 m0, s66, 0x2000
	s_nop 0
	global_load_lds_dwordx4 v[160:161], off
	v_lshl_add_u64 v[160:161], v[236:237], 0, s[48:49]
	s_mov_b32 m0, s70
	s_nop 0
	global_load_lds_dwordx4 v[160:161], off
	v_lshl_add_u64 v[160:161], v[238:239], 0, s[48:49]
	s_mov_b32 m0, s71
	s_nop 0
	global_load_lds_dwordx4 v[160:161], off
	s_waitcnt vmcnt(8)
	s_waitcnt lgkmcnt(0)
	s_barrier
	s_setprio 1
	s_waitcnt lgkmcnt(0)
	v_mfma_f32_16x16x32_bf16 v[60:63], v[138:141], v[204:207], v[60:63]
	v_mfma_f32_16x16x32_bf16 v[52:55], v[152:155], v[204:207], v[52:55]
	v_mfma_f32_16x16x32_bf16 v[44:47], v[138:141], v[212:215], v[44:47]
	v_mfma_f32_16x16x32_bf16 v[36:39], v[152:155], v[212:215], v[36:39]
	v_mfma_f32_16x16x32_bf16 v[28:31], v[138:141], v[220:223], v[28:31]
	v_mfma_f32_16x16x32_bf16 v[20:23], v[152:155], v[220:223], v[20:23]
	v_mfma_f32_16x16x32_bf16 v[12:15], v[138:141], v[228:231], v[12:15]
	v_mfma_f32_16x16x32_bf16 v[4:7], v[152:155], v[228:231], v[4:7]
	v_mfma_f32_16x16x32_bf16 v[60:63], v[148:151], v[208:211], v[60:63]
	v_mfma_f32_16x16x32_bf16 v[52:55], v[156:159], v[208:211], v[52:55]
	v_mfma_f32_16x16x32_bf16 v[44:47], v[148:151], v[216:219], v[44:47]
	v_mfma_f32_16x16x32_bf16 v[36:39], v[156:159], v[216:219], v[36:39]
	v_mfma_f32_16x16x32_bf16 v[28:31], v[148:151], v[224:227], v[28:31]
	v_mfma_f32_16x16x32_bf16 v[20:23], v[156:159], v[224:227], v[20:23]
	v_mfma_f32_16x16x32_bf16 v[12:15], v[148:151], v[232:235], v[12:15]
	v_mfma_f32_16x16x32_bf16 v[4:7], v[156:159], v[232:235], v[4:7]
	s_setprio 0
	s_setprio 1
	v_mfma_f32_16x16x32_bf16 v[56:59], v[188:191], v[204:207], v[56:59]
	v_mfma_f32_16x16x32_bf16 v[48:51], v[196:199], v[204:207], v[48:51]
	v_mfma_f32_16x16x32_bf16 v[40:43], v[188:191], v[212:215], v[40:43]
	v_mfma_f32_16x16x32_bf16 v[32:35], v[196:199], v[212:215], v[32:35]
	v_mfma_f32_16x16x32_bf16 v[24:27], v[188:191], v[220:223], v[24:27]
	v_mfma_f32_16x16x32_bf16 v[16:19], v[196:199], v[220:223], v[16:19]
	v_mfma_f32_16x16x32_bf16 v[8:11], v[188:191], v[228:231], v[8:11]
	v_mfma_f32_16x16x32_bf16 v[0:3], v[196:199], v[228:231], v[0:3]
	v_mfma_f32_16x16x32_bf16 v[56:59], v[192:195], v[208:211], v[56:59]
	v_mfma_f32_16x16x32_bf16 v[48:51], v[200:203], v[208:211], v[48:51]
	v_mfma_f32_16x16x32_bf16 v[40:43], v[192:195], v[216:219], v[40:43]
	v_mfma_f32_16x16x32_bf16 v[32:35], v[200:203], v[216:219], v[32:35]
	v_mfma_f32_16x16x32_bf16 v[24:27], v[192:195], v[224:227], v[24:27]
	v_mfma_f32_16x16x32_bf16 v[16:19], v[200:203], v[224:227], v[16:19]
	v_mfma_f32_16x16x32_bf16 v[8:11], v[192:195], v[232:235], v[8:11]
	v_mfma_f32_16x16x32_bf16 v[0:3], v[200:203], v[232:235], v[0:3]
	s_setprio 0
	s_barrier
	s_add_i32 s78, s78, 2
	s_add_u32 s76, s76, 0x100
	s_addc_u32 s77, s77, 0
	s_add_u32 s64, s64, 0x100
	s_addc_u32 s65, s65, 0
